# mla_rows: the first row's two interleaved 64-lane reductions also via DPP + permlane swaps (no ds_bpermute left in the row loop except the rope lane swap)
# baseline (speedup 1.0000x reference)
; __device__ __forceinline__ float lane_xor(float v, int lane, int o) { return __builtin_bit_cast(float, __builtin_amdgcn_ds_bpermute((lane ^ o) << 2, __builtin_bit_cast(int, v))); }
; __device__ __forceinline__ float wave_sum(float v, int lane) {
; #pragma unroll
;     for (int o = 1; o < 64; o <<= 1) v += lane_xor(v, lane, o);
;     return v;
; __device__ __forceinline__ void mla_rows(const bf16_t* U, const float* gcq, const float* gckv, const float* rope, bf16_t* XQ, bf16_t* XKV, bf16_t* KC, int gw, int ngw) {
;     ...
;         for (int k = 0; k < 2; ++k) { int r = r0 + k * ngw; r = r < MROWS ? r : r0; rr[k] = r;
;             const bf16_t* up = U + (size_t)r * DIN + 2048;
;             cq[k] = *(const u32x2*)(up + 4 * lane); ckv[k] = *(const unsigned*)(up + 256 + 2 * lane); krv[k] = bf2f(up[384 + (lane & 31)]);
;             const int s = r % LP, j = lane & 15; cs[k] = rope[(size_t)s * 32 + j]; sn[k] = rope[(size_t)s * 32 + 16 + j]; }
; #pragma unroll
;         for (int k = 0; k < 2; ++k) {
;             if (k == 1 && r0 + ngw >= MROWS) break;
;             const int r = rr[k];
;             const float q0 = __builtin_bit_cast(float, cq[k].x << 16), q1 = __builtin_bit_cast(float, cq[k].x & 0xffff0000u), q2 = __builtin_bit_cast(float, cq[k].y << 16), q3 = __builtin_bit_cast(float, cq[k].y & 0xffff0000u);
;             const float k0 = __builtin_bit_cast(float, ckv[k] << 16), k1 = __builtin_bit_cast(float, ckv[k] & 0xffff0000u);
;             const float sq = wave_sum((q0 * q0 + q1 * q1) + (q2 * q2 + q3 * q3), lane), sk = wave_sum(k0 * k0 + k1 * k1, lane);
.LBB0_642:
	s_ashr_i32 s15, s14, 31
	s_mul_i32 s6, s14, 0x1340
	s_mul_hi_i32 s7, s14, 0x1340
	s_add_u32 s6, s16, s6
	s_addc_u32 s7, s17, s7
	v_mov_b32_e32 v19, v1
	s_waitcnt lgkmcnt(0)
	v_lshl_add_u64 v[20:21], s[6:7], 0, v[18:19]
	s_movk_i32 s30, 0x1000
	s_add_u32 s8, s6, 0x1000
	v_add_co_u32_e32 v20, vcc, s30, v20
	s_addc_u32 s9, s7, 0
	v_mov_b32_e32 v17, v1
	v_addc_co_u32_e32 v21, vcc, 0, v21, vcc
	flat_load_dword v22, v[20:21] offset:512
	v_lshl_add_u64 v[20:21], s[8:9], 0, v[16:17]
	flat_load_dwordx2 v[24:25], v[20:21]
	s_mul_hi_i32 s6, s14, 0x7e07e07f
	s_lshr_b32 s7, s6, 31
	s_ashr_i32 s6, s6, 12
	s_add_i32 s6, s6, s7
	s_mulk_i32 s6, 0x2080
	v_lshl_add_u64 v[20:21], s[8:9], 0, v[0:1]
	s_sub_i32 s6, s14, s6
	flat_load_ushort v44, v[20:21] offset:768
	s_ashr_i32 s7, s6, 31
	s_add_i32 s27, s14, s26
	s_lshl_b64 s[6:7], s[6:7], 7
	s_cmp_lt_i32 s27, 0x14500
	s_cselect_b32 s8, s27, s14
	v_lshl_add_u64 v[26:27], v[8:9], 0, s[6:7]
	s_mul_i32 s6, s8, 0x1340
	s_mul_hi_i32 s7, s8, 0x1340
	s_add_u32 s6, s16, s6
	s_addc_u32 s7, s17, s7
	v_lshl_add_u64 v[20:21], s[6:7], 0, v[18:19]
	v_add_co_u32_e32 v36, vcc, s30, v20
	s_add_u32 s10, s6, 0x1000
	s_nop 0
	v_addc_co_u32_e32 v37, vcc, 0, v21, vcc
	s_addc_u32 s11, s7, 0
	s_mul_hi_i32 s9, s8, 0x7e07e07f
	s_lshr_b32 s6, s9, 31
	s_ashr_i32 s7, s9, 12
	s_add_i32 s6, s7, s6
	s_mulk_i32 s6, 0x2080
	s_sub_i32 s6, s8, s6
	s_ashr_i32 s7, s6, 31
	s_lshl_b64 s[6:7], s[6:7], 7
	v_lshl_add_u64 v[40:41], s[10:11], 0, v[0:1]
	s_waitcnt vmcnt(0) lgkmcnt(0)
	v_lshlrev_b32_e32 v20, 16, v22
	v_and_b32_e32 v21, 0xffff0000, v22
	v_lshlrev_b32_e32 v23, 16, v25
	v_lshlrev_b32_e32 v22, 16, v24
	v_and_b32_e32 v25, 0xffff0000, v25
	v_and_b32_e32 v24, 0xffff0000, v24
	v_pk_mul_f32 v[34:35], v[20:21], v[20:21]
	v_pk_mul_f32 v[38:39], v[24:25], v[24:25]
	v_add_f32_e32 v19, v34, v35
	v_pk_fma_f32 v[34:35], v[22:23], v[22:23], v[38:39]
	v_add_f32_e32 v34, v34, v35
	v_lshl_add_u64 v[38:39], s[10:11], 0, v[16:17]
	v_lshl_add_u64 v[42:43], v[8:9], 0, s[6:7]
	s_mov_b32 s6, 0xf800000
	v_add_f32_dpp v19, v19, v19 quad_perm:[1,0,3,2] row_mask:0xf bank_mask:0xf
	v_add_f32_dpp v34, v34, v34 quad_perm:[1,0,3,2] row_mask:0xf bank_mask:0xf
	s_nop 0
	v_add_f32_dpp v19, v19, v19 quad_perm:[2,3,0,1] row_mask:0xf bank_mask:0xf
	v_add_f32_dpp v34, v34, v34 quad_perm:[2,3,0,1] row_mask:0xf bank_mask:0xf
	s_nop 0
	v_add_f32_dpp v19, v19, v19 row_half_mirror row_mask:0xf bank_mask:0xf
	v_add_f32_dpp v34, v34, v34 row_half_mirror row_mask:0xf bank_mask:0xf
	s_nop 0
	v_add_f32_dpp v19, v19, v19 row_mirror row_mask:0xf bank_mask:0xf
	v_add_f32_dpp v34, v34, v34 row_mirror row_mask:0xf bank_mask:0xf
	s_nop 0
	v_mov_b32_e32 v45, v19
	v_mov_b32_e32 v47, v34
	s_nop 1
	v_permlane16_swap_b32_e32 v19, v45
	v_permlane16_swap_b32_e32 v34, v47
	v_add_f32_e32 v45, v19, v45
	v_add_f32_e32 v47, v34, v47
	v_mov_b32_e32 v46, v45
	v_mov_b32_e32 v48, v47
	s_nop 1
	v_permlane32_swap_b32_e32 v45, v46
	v_permlane32_swap_b32_e32 v47, v48
	flat_load_dword v34, v[26:27]
	flat_load_dword v35, v[26:27] offset:64
	s_nop 0
	flat_load_dwordx2 v[26:27], v[38:39]
	s_nop 0
	flat_load_dword v36, v[36:37] offset:512
	s_nop 0
	flat_load_ushort v37, v[40:41] offset:768
	flat_load_dword v17, v[42:43]
	flat_load_dword v19, v[42:43] offset:64
	v_lshlrev_b32_e32 v38, 16, v44
	s_waitcnt lgkmcnt(0)
; __device__ __forceinline__ float lane_xor(float v, int lane, int o) { return __builtin_bit_cast(float, __builtin_amdgcn_ds_bpermute((lane ^ o) << 2, __builtin_bit_cast(int, v))); }
; __device__ __forceinline__ unsigned f2bf(float f) { unsigned u = __builtin_bit_cast(unsigned, f); return (u + 0x7fffu + ((u >> 16) & 1u)) >> 16; }
; __device__ __forceinline__ unsigned pk2(float lo, float hi) { return f2bf(lo) | (f2bf(hi) << 16); }
; __device__ __forceinline__ void mla_rows(const bf16_t* U, const float* gcq, const float* gckv, const float* rope, bf16_t* XQ, bf16_t* XKV, bf16_t* KC, int gw, int ngw) {
;     ...
;             const float sq = wave_sum((q0 * q0 + q1 * q1) + (q2 * q2 + q3 * q3), lane), sk = wave_sum(k0 * k0 + k1 * k1, lane);
;             const float rq = 1.0f / sqrtf(sq * (1.0f / 256.0f) + EPSN), rk = 1.0f / sqrtf(sk * (1.0f / 128.0f) + EPSN);
;             u32x2 wq; wq.x = pk2(q0 * rq * gq.x, q1 * rq * gq.y); wq.y = pk2(q2 * rq * gq.z, q3 * rq * gq.w);
;             *(u32x2*)(XQ + (size_t)r * 256 + 4 * lane) = wq;
;             *(unsigned*)(XKV + (size_t)r * 128 + 2 * lane) = pk2(k0 * rk * gk0, k1 * rk * gk1);
;             const float other = lane_xor(krv[k], lane, 16);
;             const float ro = (lane & 16) ? (krv[k] * cs[k] + other * sn[k]) : (krv[k] * cs[k] - other * sn[k]);
;             if (lane < 32) { const unsigned short ob = (unsigned short)f2bf(ro); bf16_t* kc = KC + (size_t)r * 384 + 64 + lane;
;                 kc[0] = ob; kc[96] = ob; kc[192] = ob; kc[288] = ob; }
	v_add_f32_e32 v39, v45, v46
	v_fmamk_f32 v39, v39, 0x3c000000, v218
	v_mul_f32_e32 v41, 0x4f800000, v39
	v_add_f32_e32 v40, v47, v48
	v_cmp_gt_f32_e32 vcc, s6, v39
	v_fmamk_f32 v40, v40, 0x3b800000, v218
	v_cmp_gt_f32_e64 s[6:7], s6, v40
	v_cndmask_b32_e32 v39, v39, v41, vcc
	v_mul_f32_e32 v41, 0x4f800000, v40
	v_sqrt_f32_e32 v42, v39
	v_cndmask_b32_e64 v40, v40, v41, s[6:7]
	v_sqrt_f32_e32 v41, v40
	v_add_u32_e32 v43, -1, v42
	v_add_u32_e32 v44, 1, v42
	v_fma_f32 v45, -v43, v42, v39
	v_fma_f32 v46, -v44, v42, v39
	v_add_u32_e32 v47, -1, v41
	v_cmp_ge_f32_e64 s[10:11], 0, v45
	v_add_u32_e32 v48, 1, v41
	v_fma_f32 v45, -v48, v41, v40
	v_cndmask_b32_e64 v42, v42, v43, s[10:11]
	v_fma_f32 v43, -v47, v41, v40
	v_cmp_lt_f32_e64 s[10:11], 0, v46
	s_nop 1
	v_cndmask_b32_e64 v42, v42, v44, s[10:11]
	v_cmp_ge_f32_e64 s[10:11], 0, v43
	v_mul_f32_e32 v43, 0x37800000, v42
	v_cndmask_b32_e32 v42, v42, v43, vcc
	v_cndmask_b32_e64 v41, v41, v47, s[10:11]
	v_cmp_lt_f32_e64 s[10:11], 0, v45
	v_mov_b32_e32 v47, 0x260
	s_nop 0
	v_cndmask_b32_e64 v41, v41, v48, s[10:11]
	v_mul_f32_e32 v44, 0x37800000, v41
	v_cndmask_b32_e64 v41, v41, v44, s[6:7]
	v_cmp_class_f32_e64 s[6:7], v40, v47
	s_nop 1
	v_cndmask_b32_e64 v40, v41, v40, s[6:7]
	v_div_scale_f32 v41, s[6:7], v40, v40, 1.0
	v_rcp_f32_e32 v44, v41
	v_div_scale_f32 v43, vcc, 1.0, v40, 1.0
	v_fma_f32 v45, -v41, v44, 1.0
	v_fmac_f32_e32 v44, v45, v44
	v_mul_f32_e32 v45, v43, v44
	v_fma_f32 v46, -v41, v45, v43
	v_fmac_f32_e32 v45, v46, v44
	v_fma_f32 v41, -v41, v45, v43
	v_div_fmas_f32 v41, v41, v44, v45
	v_div_fixup_f32 v40, v41, v40, 1.0
	v_pk_mul_f32 v[22:23], v[40:41], v[22:23] op_sel_hi:[0,1]
	v_pk_mul_f32 v[22:23], v[2:3], v[22:23]
	v_cmp_class_f32_e32 vcc, v39, v47
	v_pk_mul_f32 v[24:25], v[40:41], v[24:25] op_sel_hi:[0,1]
	v_and_b32_sdwa v40, v23, v219 dst_sel:DWORD dst_unused:UNUSED_PAD src0_sel:WORD_1 src1_sel:DWORD
	v_cndmask_b32_e32 v39, v42, v39, vcc
	v_pk_mul_f32 v[24:25], v[14:15], v[24:25]
	v_and_b32_sdwa v41, v22, v219 dst_sel:DWORD dst_unused:UNUSED_PAD src0_sel:WORD_1 src1_sel:DWORD
	v_add3_u32 v23, v23, v40, s44
	v_div_scale_f32 v40, s[6:7], v39, v39, 1.0
	v_and_b32_sdwa v43, v25, v219 dst_sel:DWORD dst_unused:UNUSED_PAD src0_sel:WORD_1 src1_sel:DWORD
	v_and_b32_sdwa v44, v24, v219 dst_sel:DWORD dst_unused:UNUSED_PAD src0_sel:WORD_1 src1_sel:DWORD
	v_add3_u32 v22, v22, v41, s44
	v_rcp_f32_e32 v41, v40
	v_add3_u32 v25, v25, v43, s44
	v_add3_u32 v24, v24, v44, s44
	v_and_b32_e32 v25, 0xffff0000, v25
	v_and_b32_e32 v24, 0xffff0000, v24
	s_lshl_b64 s[6:7], s[14:15], 9
	v_or_b32_sdwa v23, v25, v23 dst_sel:DWORD dst_unused:UNUSED_PAD src0_sel:DWORD src1_sel:WORD_1
	v_or_b32_sdwa v22, v24, v22 dst_sel:DWORD dst_unused:UNUSED_PAD src0_sel:DWORD src1_sel:WORD_1
	v_lshl_add_u64 v[24:25], v[12:13], 0, s[6:7]
	flat_store_dwordx2 v[24:25], v[22:23]
	v_fma_f32 v22, -v40, v41, 1.0
	v_fmac_f32_e32 v41, v22, v41
	v_div_scale_f32 v22, vcc, 1.0, v39, 1.0
	v_mul_f32_e32 v23, v22, v41
	v_fma_f32 v24, -v40, v23, v22
	v_fmac_f32_e32 v23, v24, v41
	v_fma_f32 v22, -v40, v23, v22
	v_div_fmas_f32 v22, v22, v41, v23
	v_div_fixup_f32 v22, v22, v39, 1.0
	v_pk_mul_f32 v[20:21], v[22:23], v[20:21] op_sel_hi:[0,1]
	v_pk_mul_f32 v[20:21], v[6:7], v[20:21]
	s_lshl_b64 s[6:7], s[14:15], 8
	v_and_b32_sdwa v23, v20, v219 dst_sel:DWORD dst_unused:UNUSED_PAD src0_sel:WORD_1 src1_sel:DWORD
	v_and_b32_sdwa v22, v21, v219 dst_sel:DWORD dst_unused:UNUSED_PAD src0_sel:WORD_1 src1_sel:DWORD
	v_add3_u32 v20, v20, v23, s44
	v_add3_u32 v21, v21, v22, s44
	v_lshrrev_b32_e32 v22, 16, v20
	ds_bpermute_b32 v20, v32, v38
	v_and_or_b32 v21, v21, s49, v22
	v_lshl_add_u64 v[22:23], v[10:11], 0, s[6:7]
	flat_store_dword v[22:23], v21
	s_and_saveexec_b64 s[6:7], s[4:5]
	s_cbranch_execnz .LBB0_644
	s_or_b64 exec, exec, s[6:7]
	s_cmp_gt_i32 s27, 0x144ff
	s_cbranch_scc1 .LBB0_641
	s_branch .LBB0_645
